# in-proj K-loop: first two counted waits after a unit's output stores leave those stores in flight (vmcnt 24 instead of 8)
# baseline (speedup 1.0000x reference)
; #define PG8_STAGE(bufoff, gbase, voff) do { _Pragma("unroll") for (int _i = 0; _i < 2; ++_i) \
;         __builtin_amdgcn_global_load_lds((const unsigned*)((const char*)(gbase) + (voff)[_i]), (LAS unsigned*)(lds + (bufoff) + ldsw + _i * 8192), 16, 0, 0); } while (0)
; #define PG8_WAIT_V(n) asm volatile("s_waitcnt vmcnt(" #n ")" ::: "memory")
; #define PG8_BAR __builtin_amdgcn_s_barrier()
; template <class Epi>
; __device__ __forceinline__ void gemm_phase(LAS unsigned char* lds, const Gemm g, const int G, const int cidx, const Epi& E) {
;     ...
;     for (int i = 0; i < 2; ++i) { int R, C; stage_rc(tid * 16 + i * 8192, R, C); const int Rb = Epi::PERM ? ((R & ~31) + perm32(R & 31)) : R;
;         voffA[i] = (unsigned)(R * K + C) * 2u; voffB[i] = (unsigned)(Rb * K + C) * 2u; }
;     const size_t kstep = (size_t)(BK * 2);
;     const size_t hstep = (size_t)HALF * K * 2;
;     const size_t tstep = 2 * hstep;
;     const unsigned ldsw = (unsigned)wid * 1024u;
;     const int aoff = lds_byte(wr * 64 + fr, fq * 8), boff = lds_byte(wc * 32 + fr, fq * 8);
;     ...
;     Unit cur, nxt; int ui = 0;
;     if (!S.next(0, cur)) return;
;     f32x4 acc[2][2][4][2];
; #pragma unroll
;     for (int a = 0; a < 2; ++a)
; #pragma unroll
;         for (int b = 0; b < 2; ++b)
; #pragma unroll
;             for (int m = 0; m < 4; ++m)
; #pragma unroll
;                 for (int n = 0; n < 2; ++n) acc[a][b][m][n] = ZERO4;
;     bf16x8 At[4][2], B0[2][2], B1[2][2];
;     const char* cA = PG8_ABASE(cur); const char* cB = (const char*)g.Bt + (size_t)cur.pn * tstep;
;     PG8_STAGE(PG8_SB(0, 0), cB, voffB); PG8_STAGE(PG8_SB(0, 1), cB + hstep, voffB); PG8_STAGE(PG8_SA(0, 0), cA, voffA); PG8_STAGE(PG8_SA(0, 1), cA + hstep, voffA);
;     if (wr == 1) PG8_BAR;
;     PG8_WAIT_V(2); PG8_BAR;
;     PG8_STAGE(PG8_SB(1, 0), cB + kstep, voffB); PG8_STAGE(PG8_SA(1, 0), cA + kstep, voffA); PG8_STAGE(PG8_SB(1, 1), cB + hstep + kstep, voffB);
;     PG8_WAIT_V(6); PG8_BAR;
.LBB0_596:
	s_and_b32 s10, s8, 3
	s_add_i32 m0, s97, 0x18000
	v_lshl_add_u64 v[10:11], v[10:11], 0, s[46:47]
	s_lshl_b32 s11, s5, 13
	s_lshl_b32 s12, s10, 12
	s_waitcnt vmcnt(2)
	s_barrier
	global_load_lds_dwordx4 v[10:11], off
	v_lshl_add_u64 v[8:9], v[8:9], 0, s[46:47]
	s_add_i32 m0, s97, 0x1a000
	s_add_i32 s84, s97, 0x8000
	s_add_i32 s76, s97, 0xa000
	global_load_lds_dwordx4 v[8:9], off
	v_lshl_add_u64 v[6:7], v[6:7], 0, s[46:47]
	s_mov_b32 m0, s84
	s_add_u32 s8, s20, 0x40080
	global_load_lds_dwordx4 v[6:7], off
	v_lshl_add_u64 v[4:5], v[4:5], 0, s[46:47]
	s_mov_b32 m0, s76
	s_addc_u32 s9, s21, 0
	global_load_lds_dwordx4 v[4:5], off
	s_add_i32 m0, s97, 0x1c000
	v_lshl_add_u64 v[4:5], s[8:9], 0, v[148:149]
	global_load_lds_dwordx4 v[4:5], off
	v_lshl_add_u64 v[4:5], s[8:9], 0, v[0:1]
	s_add_i32 m0, s97, 0x1e000
	s_sext_i32_i16 s35, s4
	global_load_lds_dwordx4 v[4:5], off
	v_and_b32_e32 v4, 15, v12
	v_bfe_u32 v5, v12, 4, 2
	v_lshl_or_b32 v3, s5, 6, v4
	s_lshl_b32 s4, s5, 10
	s_lshl_b32 s5, s10, 6
	v_lshlrev_b32_e32 v6, 3, v5
	v_lshlrev_b32_e32 v5, 4, v5
	s_or_b32 s4, s5, s4
	v_lshl_or_b32 v7, v4, 6, v5
	v_or3_b32 v4, s4, v5, v4
	v_ashrrev_i32_e32 v5, 31, v4
	v_lshl_add_u64 v[4:5], v[4:5], 4, s[6:7]
	s_mov_b64 s[4:5], 0x5800000
	v_lshl_add_u64 v[152:153], v[4:5], 0, s[4:5]
	v_lshlrev_b32_e32 v4, 14, v13
	v_and_b32_e32 v4, 0xffff8000, v4
	v_lshl_add_u32 v4, v14, 11, v4
	v_and_b32_e32 v5, 1, v13
	v_lshl_or_b32 v4, v5, 6, v4
	v_lshl_add_u32 v154, v15, 1, v4
	v_lshlrev_b32_e32 v4, 14, v17
	v_lshlrev_b32_e32 v8, 2, v12
	v_and_b32_e32 v4, 0xffff8000, v4
	v_and_b32_e32 v8, 32, v8
	s_waitcnt vmcnt(6)
	v_lshl_add_u32 v4, v16, 11, v4
	v_and_b32_e32 v5, 1, v17
	v_bitop3_b32 v9, v7, s11, v8 bitop3:0xde
	v_lshl_or_b32 v4, v5, 6, v4
	v_bitop3_b32 v145, v7, s12, v8 bitop3:0xde
	s_ashr_i32 s31, s3, 31
	v_lshl_or_b32 v162, s10, 5, v6
	v_mov_b32_e32 v155, v2
	v_lshl_add_u32 v156, v18, 1, v4
	v_mov_b32_e32 v157, v2
	s_mov_b32 s34, 0
	v_add_u32_e32 v163, 0, v9
	s_barrier
	s_mov_b32 s98, 0
	s_branch .LBB0_598
.LBB0_597:
	s_mov_b32 s98, 1
	s_and_b64 vcc, exec, s[4:5]
	s_mov_b32 s35, s8
	s_mov_b32 s18, s10
	s_mov_b64 s[20:21], s[14:15]
	s_mov_b64 s[24:25], s[12:13]
	s_cbranch_vccnz .LBB0_606

; #define PG8_STAGE(bufoff, gbase, voff) do { _Pragma("unroll") for (int _i = 0; _i < 2; ++_i) \
;         __builtin_amdgcn_global_load_lds((const unsigned*)((const char*)(gbase) + (voff)[_i]), (LAS unsigned*)(lds + (bufoff) + ldsw + _i * 8192), 16, 0, 0); } while (0)
; #define PG8_LDA(dst, b, h) do { _Pragma("unroll") for (int m = 0; m < 4; ++m) _Pragma("unroll") for (int k = 0; k < 2; ++k) dst[m][k] = *(const LAS bf16x8*)(lds + PG8_SA(b, h) + aoff + m * 2048 + k * 1024); } while (0)
; #define PG8_LDB(dst, b, h) do { _Pragma("unroll") for (int n = 0; n < 2; ++n) _Pragma("unroll") for (int k = 0; k < 2; ++k) dst[n][k] = *(const LAS bf16x8*)(lds + PG8_SB(b, h) + boff + n * 2048 + k * 1024); } while (0)
; #define PG8_MMA(ai, bj, At, Bt) do { __builtin_amdgcn_s_setprio(1); _Pragma("unroll") for (int m = 0; m < 4; ++m) _Pragma("unroll") for (int n = 0; n < 2; ++n) _Pragma("unroll") for (int k = 0; k < 2; ++k) \
;         acc[ai][bj][m][n] = __builtin_amdgcn_mfma_f32_16x16x32_bf16(Bt[n][k], At[m][k], acc[ai][bj][m][n], 0, 0, 0); __builtin_amdgcn_s_setprio(0); } while (0)
; #define PG8_WAIT_V(n) asm volatile("s_waitcnt vmcnt(" #n ")" ::: "memory")
; #define PG8_WAIT_L(n) asm volatile("s_waitcnt lgkmcnt(" #n ")" ::: "memory")
; #define PG8_BAR __builtin_amdgcn_s_barrier()
; #define PG8_SCHED __builtin_amdgcn_sched_barrier(0)
; template <class Epi>
; __device__ __forceinline__ void gemm_phase(LAS unsigned char* lds, const Gemm g, const int G, const int cidx, const Epi& E) {
;     ...
;         for (int t = 0; t < nt; t += 2) {
;             const bool last = (t == nt - 2);
;             const char* a1 = cA + (size_t)(t + 1) * kstep;
;             const char* a2 = last ? nA : cA + (size_t)(t + 2) * kstep; const char* b2 = last ? nB : cB + (size_t)(t + 2) * kstep;
;             const char* a3 = a2 + kstep; const char* b3 = b2 + kstep;
;             PG8_LDB(B0, 0, 0); PG8_LDB(B1, 0, 1); PG8_SCHED; PG8_LDA(At, 0, 0); PG8_STAGE(PG8_SA(1, 1), a1 + hstep, voffA);
;             PG8_WAIT_V(8); PG8_WAIT_L(0); PG8_BAR; PG8_MMA(0, 0, At, B0); PG8_MMA(0, 1, At, B1); PG8_BAR; PG8_SCHED;
;             PG8_LDA(At, 0, 1); PG8_STAGE(PG8_SB(0, 0), b2, voffB); PG8_STAGE(PG8_SB(0, 1), b2 + hstep, voffB); PG8_STAGE(PG8_SA(0, 0), a2, voffA);
;             PG8_WAIT_V(8); PG8_WAIT_L(0); PG8_BAR; PG8_MMA(1, 0, At, B0); PG8_MMA(1, 1, At, B1); PG8_BAR; PG8_SCHED;
.LBB0_601:
	s_add_u32 s24, s20, 0xfffc0080
	s_addc_u32 s25, s21, -1
	s_add_i32 s43, 0, 0x10000
	s_cmp_eq_u32 s45, 12
	s_cselect_b32 s27, s11, s25
	s_cselect_b32 s26, s19, s24
	v_add_u32_e32 v132, s43, v145
	s_cselect_b32 s25, s9, s44
	s_cselect_b32 s24, s33, s42
	s_add_i32 s68, 0, 0x14000
	ds_read_b128 v[158:161], v132
	ds_read_b128 v[164:167], v132 offset:1024
	ds_read_b128 v[168:171], v132 offset:2048
	ds_read_b128 v[172:175], v132 offset:3072
	v_add_u32_e32 v132, s68, v145
	ds_read_b128 v[176:179], v132
	ds_read_b128 v[180:183], v132 offset:1024
	ds_read_b128 v[184:187], v132 offset:2048
	ds_read_b128 v[188:191], v132 offset:3072
	v_lshl_add_u64 v[132:133], s[20:21], 0, v[156:157]
	s_add_i32 m0, s97, 0xc000
	ds_read_b128 v[192:195], v163
	ds_read_b128 v[196:199], v163 offset:1024
	ds_read_b128 v[214:217], v163 offset:2048
	ds_read_b128 v[218:221], v163 offset:3072
	ds_read_b128 v[222:225], v163 offset:4096
	ds_read_b128 v[226:229], v163 offset:5120
	ds_read_b128 v[230:233], v163 offset:6144
	ds_read_b128 v[234:237], v163 offset:7168
	global_load_lds_dwordx4 v[132:133], off
	v_lshl_add_u64 v[132:133], s[20:21], 0, v[154:155]
	s_add_i32 m0, s97, 0xe000
	s_nop 0
	global_load_lds_dwordx4 v[132:133], off
	s_cmp_eq_u32 s98, 1
	s_cbranch_scc1 .Lrelax_w1
	s_waitcnt vmcnt(8)
.Lrelax_w1:
	s_waitcnt vmcnt(24)
	s_waitcnt lgkmcnt(0)
	s_barrier
	s_setprio 1
	s_waitcnt lgkmcnt(0)
	v_mfma_f32_16x16x32_bf16 v[128:131], v[158:161], v[192:195], v[128:131]
	v_mfma_f32_16x16x32_bf16 v[124:127], v[168:171], v[192:195], v[124:127]
	v_mfma_f32_16x16x32_bf16 v[120:123], v[158:161], v[214:217], v[120:123]
	v_mfma_f32_16x16x32_bf16 v[112:115], v[168:171], v[214:217], v[112:115]
	v_mfma_f32_16x16x32_bf16 v[104:107], v[158:161], v[222:225], v[104:107]
	v_mfma_f32_16x16x32_bf16 v[96:99], v[168:171], v[222:225], v[96:99]
	v_mfma_f32_16x16x32_bf16 v[88:91], v[158:161], v[230:233], v[88:91]
	v_mfma_f32_16x16x32_bf16 v[80:83], v[168:171], v[230:233], v[80:83]
	v_mfma_f32_16x16x32_bf16 v[128:131], v[164:167], v[196:199], v[128:131]
	v_mfma_f32_16x16x32_bf16 v[124:127], v[172:175], v[196:199], v[124:127]
	v_mfma_f32_16x16x32_bf16 v[120:123], v[164:167], v[218:221], v[120:123]
	v_mfma_f32_16x16x32_bf16 v[112:115], v[172:175], v[218:221], v[112:115]
	v_mfma_f32_16x16x32_bf16 v[104:107], v[164:167], v[226:229], v[104:107]
	v_mfma_f32_16x16x32_bf16 v[96:99], v[172:175], v[226:229], v[96:99]
	v_mfma_f32_16x16x32_bf16 v[88:91], v[164:167], v[234:237], v[88:91]
	v_mfma_f32_16x16x32_bf16 v[80:83], v[172:175], v[234:237], v[80:83]
	s_setprio 0
	s_setprio 1
	v_mfma_f32_16x16x32_bf16 v[116:119], v[176:179], v[192:195], v[116:119]
	v_mfma_f32_16x16x32_bf16 v[108:111], v[184:187], v[192:195], v[108:111]
	v_mfma_f32_16x16x32_bf16 v[100:103], v[176:179], v[214:217], v[100:103]
	v_mfma_f32_16x16x32_bf16 v[92:95], v[184:187], v[214:217], v[92:95]
	v_mfma_f32_16x16x32_bf16 v[84:87], v[176:179], v[222:225], v[84:87]
	v_mfma_f32_16x16x32_bf16 v[76:79], v[184:187], v[222:225], v[76:79]
	v_mfma_f32_16x16x32_bf16 v[72:75], v[176:179], v[230:233], v[72:75]
	v_mfma_f32_16x16x32_bf16 v[68:71], v[184:187], v[230:233], v[68:71]
	v_mfma_f32_16x16x32_bf16 v[116:119], v[180:183], v[196:199], v[116:119]
	v_mfma_f32_16x16x32_bf16 v[108:111], v[188:191], v[196:199], v[108:111]
	v_mfma_f32_16x16x32_bf16 v[100:103], v[180:183], v[218:221], v[100:103]
	v_mfma_f32_16x16x32_bf16 v[92:95], v[188:191], v[218:221], v[92:95]
	v_mfma_f32_16x16x32_bf16 v[84:87], v[180:183], v[226:229], v[84:87]
	v_mfma_f32_16x16x32_bf16 v[76:79], v[188:191], v[226:229], v[76:79]
	v_mfma_f32_16x16x32_bf16 v[72:75], v[180:183], v[234:237], v[72:75]
	v_mfma_f32_16x16x32_bf16 v[68:71], v[188:191], v[234:237], v[68:71]
	s_setprio 0
	s_barrier
	s_add_i32 s43, s43, s95
	v_lshl_add_u64 v[132:133], s[24:25], 0, v[148:149]
	s_mov_b32 m0, s43
	ds_read_b128 v[192:195], v163 offset:16384
	ds_read_b128 v[196:199], v163 offset:17408
	ds_read_b128 v[214:217], v163 offset:18432
	ds_read_b128 v[218:221], v163 offset:19456
	ds_read_b128 v[222:225], v163 offset:20480
	ds_read_b128 v[226:229], v163 offset:21504
	ds_read_b128 v[230:233], v163 offset:22528
	ds_read_b128 v[234:237], v163 offset:23552
	global_load_lds_dwordx4 v[132:133], off
	s_add_i32 m0, s43, 0x2000
	s_add_u32 s86, s24, 0x40000
	v_lshl_add_u64 v[134:135], s[24:25], 0, v[0:1]
	s_addc_u32 s87, s25, 0
	s_add_i32 s43, s68, s95
	global_load_lds_dwordx4 v[134:135], off
	v_lshl_add_u64 v[140:141], s[86:87], 0, v[148:149]
	s_mov_b32 m0, s43
	v_lshl_add_u64 v[142:143], s[26:27], 0, v[146:147]
	global_load_lds_dwordx4 v[140:141], off
	v_lshl_add_u64 v[140:141], s[86:87], 0, v[0:1]
	s_add_i32 m0, s43, 0x2000
	s_nop 0
	global_load_lds_dwordx4 v[140:141], off
	v_lshl_add_u64 v[140:141], s[26:27], 0, v[150:151]
	s_mov_b32 m0, s97
	s_nop 0
	global_load_lds_dwordx4 v[140:141], off
	s_mov_b32 m0, s22
	s_nop 0
	global_load_lds_dwordx4 v[142:143], off
	s_cmp_eq_u32 s98, 1
	s_cbranch_scc1 .Lrelax_w2
	s_waitcnt vmcnt(8)
; #define PG8_STAGE(bufoff, gbase, voff) do { _Pragma("unroll") for (int _i = 0; _i < 2; ++_i) \
;         __builtin_amdgcn_global_load_lds((const unsigned*)((const char*)(gbase) + (voff)[_i]), (LAS unsigned*)(lds + (bufoff) + ldsw + _i * 8192), 16, 0, 0); } while (0)
; #define PG8_LDA(dst, b, h) do { _Pragma("unroll") for (int m = 0; m < 4; ++m) _Pragma("unroll") for (int k = 0; k < 2; ++k) dst[m][k] = *(const LAS bf16x8*)(lds + PG8_SA(b, h) + aoff + m * 2048 + k * 1024); } while (0)
; #define PG8_LDB(dst, b, h) do { _Pragma("unroll") for (int n = 0; n < 2; ++n) _Pragma("unroll") for (int k = 0; k < 2; ++k) dst[n][k] = *(const LAS bf16x8*)(lds + PG8_SB(b, h) + boff + n * 2048 + k * 1024); } while (0)
; #define PG8_MMA(ai, bj, At, Bt) do { __builtin_amdgcn_s_setprio(1); _Pragma("unroll") for (int m = 0; m < 4; ++m) _Pragma("unroll") for (int n = 0; n < 2; ++n) _Pragma("unroll") for (int k = 0; k < 2; ++k) \
;         acc[ai][bj][m][n] = __builtin_amdgcn_mfma_f32_16x16x32_bf16(Bt[n][k], At[m][k], acc[ai][bj][m][n], 0, 0, 0); __builtin_amdgcn_s_setprio(0); } while (0)
; #define PG8_WAIT_V(n) asm volatile("s_waitcnt vmcnt(" #n ")" ::: "memory")
; #define PG8_WAIT_L(n) asm volatile("s_waitcnt lgkmcnt(" #n ")" ::: "memory")
; #define PG8_BAR __builtin_amdgcn_s_barrier()
; #define PG8_SCHED __builtin_amdgcn_sched_barrier(0)
; template <class Epi>
; __device__ __forceinline__ void gemm_phase(LAS unsigned char* lds, const Gemm g, const int G, const int cidx, const Epi& E) {
;     ...
;             PG8_WAIT_V(8); PG8_WAIT_L(0); PG8_BAR; PG8_MMA(0, 0, At, B0); PG8_MMA(0, 1, At, B1); PG8_BAR; PG8_SCHED;
;             PG8_LDA(At, 0, 1); PG8_STAGE(PG8_SB(0, 0), b2, voffB); PG8_STAGE(PG8_SB(0, 1), b2 + hstep, voffB); PG8_STAGE(PG8_SA(0, 0), a2, voffA);
;             PG8_WAIT_V(8); PG8_WAIT_L(0); PG8_BAR; PG8_MMA(1, 0, At, B0); PG8_MMA(1, 1, At, B1); PG8_BAR; PG8_SCHED;
;             PG8_LDB(B0, 1, 0); PG8_LDB(B1, 1, 1); PG8_SCHED; PG8_LDA(At, 1, 0); PG8_STAGE(PG8_SA(0, 1), a2 + hstep, voffA);
;             PG8_WAIT_V(8); PG8_WAIT_L(0); PG8_BAR; PG8_MMA(0, 0, At, B0); PG8_MMA(0, 1, At, B1); PG8_BAR; PG8_SCHED;
.Lrelax_w2:
	s_waitcnt vmcnt(24)
	s_mov_b32 s98, 0
	s_waitcnt lgkmcnt(0)
	s_barrier
	s_setprio 1
	s_waitcnt lgkmcnt(0)
	v_mfma_f32_16x16x32_bf16 v[64:67], v[158:161], v[192:195], v[64:67]
	v_mfma_f32_16x16x32_bf16 v[60:63], v[168:171], v[192:195], v[60:63]
	v_mfma_f32_16x16x32_bf16 v[56:59], v[158:161], v[214:217], v[56:59]
	v_mfma_f32_16x16x32_bf16 v[48:51], v[168:171], v[214:217], v[48:51]
	v_mfma_f32_16x16x32_bf16 v[40:43], v[158:161], v[222:225], v[40:43]
	v_mfma_f32_16x16x32_bf16 v[32:35], v[168:171], v[222:225], v[32:35]
	v_mfma_f32_16x16x32_bf16 v[24:27], v[158:161], v[230:233], v[24:27]
	v_mfma_f32_16x16x32_bf16 v[16:19], v[168:171], v[230:233], v[16:19]
	v_mfma_f32_16x16x32_bf16 v[64:67], v[164:167], v[196:199], v[64:67]
	v_mfma_f32_16x16x32_bf16 v[60:63], v[172:175], v[196:199], v[60:63]
	v_mfma_f32_16x16x32_bf16 v[56:59], v[164:167], v[218:221], v[56:59]
	v_mfma_f32_16x16x32_bf16 v[48:51], v[172:175], v[218:221], v[48:51]
	v_mfma_f32_16x16x32_bf16 v[40:43], v[164:167], v[226:229], v[40:43]
	v_mfma_f32_16x16x32_bf16 v[32:35], v[172:175], v[226:229], v[32:35]
	v_mfma_f32_16x16x32_bf16 v[24:27], v[164:167], v[234:237], v[24:27]
	v_mfma_f32_16x16x32_bf16 v[16:19], v[172:175], v[234:237], v[16:19]
	s_setprio 0
	s_setprio 1
	v_mfma_f32_16x16x32_bf16 v[52:55], v[176:179], v[192:195], v[52:55]
	v_mfma_f32_16x16x32_bf16 v[44:47], v[184:187], v[192:195], v[44:47]
	v_mfma_f32_16x16x32_bf16 v[36:39], v[176:179], v[214:217], v[36:39]
	v_mfma_f32_16x16x32_bf16 v[28:31], v[184:187], v[214:217], v[28:31]
	v_mfma_f32_16x16x32_bf16 v[20:23], v[176:179], v[222:225], v[20:23]
	v_mfma_f32_16x16x32_bf16 v[12:15], v[184:187], v[222:225], v[12:15]
	v_mfma_f32_16x16x32_bf16 v[8:11], v[176:179], v[230:233], v[8:11]
	v_mfma_f32_16x16x32_bf16 v[4:7], v[184:187], v[230:233], v[4:7]
	v_mfma_f32_16x16x32_bf16 v[52:55], v[180:183], v[196:199], v[52:55]
	v_mfma_f32_16x16x32_bf16 v[44:47], v[188:191], v[196:199], v[44:47]
	v_mfma_f32_16x16x32_bf16 v[36:39], v[180:183], v[218:221], v[36:39]
	v_mfma_f32_16x16x32_bf16 v[28:31], v[188:191], v[218:221], v[28:31]
	v_mfma_f32_16x16x32_bf16 v[20:23], v[180:183], v[226:229], v[20:23]
	v_mfma_f32_16x16x32_bf16 v[12:15], v[188:191], v[226:229], v[12:15]
	v_mfma_f32_16x16x32_bf16 v[8:11], v[180:183], v[234:237], v[8:11]
	v_mfma_f32_16x16x32_bf16 v[4:7], v[188:191], v[234:237], v[4:7]
	s_setprio 0
	s_barrier
	s_add_i32 s43, 0, 0x18000
	s_add_i32 s68, 0, 0x1c000
	v_add_u32_e32 v172, s43, v145
	v_add_u32_e32 v188, s68, v145
	ds_read_b128 v[158:161], v172
	ds_read_b128 v[164:167], v172 offset:1024
	ds_read_b128 v[168:171], v172 offset:2048
	ds_read_b128 v[172:175], v172 offset:3072
	ds_read_b128 v[176:179], v188
	ds_read_b128 v[180:183], v188 offset:1024
	ds_read_b128 v[184:187], v188 offset:2048
	ds_read_b128 v[188:191], v188 offset:3072
	s_add_u32 s26, s26, 0x40000
	s_addc_u32 s27, s27, 0
	s_mov_b32 m0, s16
	v_lshl_add_u64 v[200:201], s[26:27], 0, v[150:151]
	ds_read_b128 v[192:195], v163 offset:32768
	ds_read_b128 v[196:199], v163 offset:33792
	ds_read_b128 v[214:217], v163 offset:34816
	ds_read_b128 v[218:221], v163 offset:35840
	ds_read_b128 v[222:225], v163 offset:36864
	ds_read_b128 v[226:229], v163 offset:37888
	ds_read_b128 v[230:233], v163 offset:38912
	ds_read_b128 v[234:237], v163 offset:39936
	global_load_lds_dwordx4 v[200:201], off
	v_lshl_add_u64 v[200:201], s[26:27], 0, v[146:147]
	s_mov_b32 m0, s17
	s_nop 0
	global_load_lds_dwordx4 v[200:201], off
	s_waitcnt vmcnt(8)
	s_waitcnt lgkmcnt(0)
	s_barrier
	s_setprio 1
	s_waitcnt lgkmcnt(0)
	v_mfma_f32_16x16x32_bf16 v[128:131], v[158:161], v[192:195], v[128:131]
	v_mfma_f32_16x16x32_bf16 v[124:127], v[168:171], v[192:195], v[124:127]
	v_mfma_f32_16x16x32_bf16 v[120:123], v[158:161], v[214:217], v[120:123]
	v_mfma_f32_16x16x32_bf16 v[112:115], v[168:171], v[214:217], v[112:115]
	v_mfma_f32_16x16x32_bf16 v[104:107], v[158:161], v[222:225], v[104:107]
	v_mfma_f32_16x16x32_bf16 v[96:99], v[168:171], v[222:225], v[96:99]
	v_mfma_f32_16x16x32_bf16 v[88:91], v[158:161], v[230:233], v[88:91]
	v_mfma_f32_16x16x32_bf16 v[80:83], v[168:171], v[230:233], v[80:83]
	v_mfma_f32_16x16x32_bf16 v[128:131], v[164:167], v[196:199], v[128:131]
	v_mfma_f32_16x16x32_bf16 v[124:127], v[172:175], v[196:199], v[124:127]
	v_mfma_f32_16x16x32_bf16 v[120:123], v[164:167], v[218:221], v[120:123]
	v_mfma_f32_16x16x32_bf16 v[112:115], v[172:175], v[218:221], v[112:115]
	v_mfma_f32_16x16x32_bf16 v[104:107], v[164:167], v[226:229], v[104:107]
	v_mfma_f32_16x16x32_bf16 v[96:99], v[172:175], v[226:229], v[96:99]
	v_mfma_f32_16x16x32_bf16 v[88:91], v[164:167], v[234:237], v[88:91]
	v_mfma_f32_16x16x32_bf16 v[80:83], v[172:175], v[234:237], v[80:83]
	s_setprio 0
	s_setprio 1
	v_mfma_f32_16x16x32_bf16 v[116:119], v[176:179], v[192:195], v[116:119]
	v_mfma_f32_16x16x32_bf16 v[108:111], v[184:187], v[192:195], v[108:111]
	v_mfma_f32_16x16x32_bf16 v[100:103], v[176:179], v[214:217], v[100:103]
	v_mfma_f32_16x16x32_bf16 v[92:95], v[184:187], v[214:217], v[92:95]
	v_mfma_f32_16x16x32_bf16 v[84:87], v[176:179], v[222:225], v[84:87]
	v_mfma_f32_16x16x32_bf16 v[76:79], v[184:187], v[222:225], v[76:79]
	v_mfma_f32_16x16x32_bf16 v[72:75], v[176:179], v[230:233], v[72:75]
	v_mfma_f32_16x16x32_bf16 v[68:71], v[184:187], v[230:233], v[68:71]
	v_mfma_f32_16x16x32_bf16 v[116:119], v[180:183], v[196:199], v[116:119]
	v_mfma_f32_16x16x32_bf16 v[108:111], v[188:191], v[196:199], v[108:111]
	v_mfma_f32_16x16x32_bf16 v[100:103], v[180:183], v[218:221], v[100:103]
	v_mfma_f32_16x16x32_bf16 v[92:95], v[188:191], v[218:221], v[92:95]
	v_mfma_f32_16x16x32_bf16 v[84:87], v[180:183], v[226:229], v[84:87]
	v_mfma_f32_16x16x32_bf16 v[76:79], v[188:191], v[226:229], v[76:79]
	v_mfma_f32_16x16x32_bf16 v[72:75], v[180:183], v[234:237], v[72:75]
	v_mfma_f32_16x16x32_bf16 v[68:71], v[188:191], v[234:237], v[68:71]
	s_setprio 0
	s_barrier
; #define PG8_STAGE(bufoff, gbase, voff) do { _Pragma("unroll") for (int _i = 0; _i < 2; ++_i) \
;         __builtin_amdgcn_global_load_lds((const unsigned*)((const char*)(gbase) + (voff)[_i]), (LAS unsigned*)(lds + (bufoff) + ldsw + _i * 8192), 16, 0, 0); } while (0)
; #define PG8_LDA(dst, b, h) do { _Pragma("unroll") for (int m = 0; m < 4; ++m) _Pragma("unroll") for (int k = 0; k < 2; ++k) dst[m][k] = *(const LAS bf16x8*)(lds + PG8_SA(b, h) + aoff + m * 2048 + k * 1024); } while (0)
; #define PG8_LDB(dst, b, h) do { _Pragma("unroll") for (int n = 0; n < 2; ++n) _Pragma("unroll") for (int k = 0; k < 2; ++k) dst[n][k] = *(const LAS bf16x8*)(lds + PG8_SB(b, h) + boff + n * 2048 + k * 1024); } while (0)
; #define PG8_MMA(ai, bj, At, Bt) do { __builtin_amdgcn_s_setprio(1); _Pragma("unroll") for (int m = 0; m < 4; ++m) _Pragma("unroll") for (int n = 0; n < 2; ++n) _Pragma("unroll") for (int k = 0; k < 2; ++k) \
;         acc[ai][bj][m][n] = __builtin_amdgcn_mfma_f32_16x16x32_bf16(Bt[n][k], At[m][k], acc[ai][bj][m][n], 0, 0, 0); __builtin_amdgcn_s_setprio(0); } while (0)
; #define PG8_WAIT_V(n) asm volatile("s_waitcnt vmcnt(" #n ")" ::: "memory")
; #define PG8_WAIT_L(n) asm volatile("s_waitcnt lgkmcnt(" #n ")" ::: "memory")
; #define PG8_BAR __builtin_amdgcn_s_barrier()
; #define PG8_SCHED __builtin_amdgcn_sched_barrier(0)
; template <class Epi>
; __device__ __forceinline__ void gemm_phase(LAS unsigned char* lds, const Gemm g, const int G, const int cidx, const Epi& E) {
;     ...
;             PG8_LDB(B0, 1, 0); PG8_LDB(B1, 1, 1); PG8_SCHED; PG8_LDA(At, 1, 0); PG8_STAGE(PG8_SA(0, 1), a2 + hstep, voffA);
;             PG8_WAIT_V(8); PG8_WAIT_L(0); PG8_BAR; PG8_MMA(0, 0, At, B0); PG8_MMA(0, 1, At, B1); PG8_BAR; PG8_SCHED;
;             PG8_LDA(At, 1, 1); PG8_STAGE(PG8_SB(1, 0), b3, voffB); PG8_STAGE(PG8_SB(1, 1), b3 + hstep, voffB); PG8_STAGE(PG8_SA(1, 0), a3, voffA);
;             PG8_WAIT_V(8); PG8_WAIT_L(0); PG8_BAR; PG8_MMA(1, 0, At, B0); PG8_MMA(1, 1, At, B1); PG8_BAR; PG8_SCHED;
;         }
	s_add_i32 s26, s43, s95
	v_lshl_add_u64 v[132:133], v[132:133], 0, s[46:47]
	s_mov_b32 m0, s26
	ds_read_b128 v[192:195], v163 offset:49152
	ds_read_b128 v[196:199], v163 offset:50176
	ds_read_b128 v[214:217], v163 offset:51200
	ds_read_b128 v[218:221], v163 offset:52224
	ds_read_b128 v[222:225], v163 offset:53248
	ds_read_b128 v[226:229], v163 offset:54272
	ds_read_b128 v[230:233], v163 offset:55296
	ds_read_b128 v[234:237], v163 offset:56320
	global_load_lds_dwordx4 v[132:133], off
	s_add_i32 m0, s26, 0x2000
	s_add_u32 s24, s24, 0x40080
	v_lshl_add_u64 v[132:133], v[134:135], 0, s[46:47]
	s_addc_u32 s25, s25, 0
	s_add_i32 s26, s68, s95
	global_load_lds_dwordx4 v[132:133], off
	v_lshl_add_u64 v[132:133], s[24:25], 0, v[148:149]
	s_mov_b32 m0, s26
	s_nop 0
	global_load_lds_dwordx4 v[132:133], off
	v_lshl_add_u64 v[132:133], s[24:25], 0, v[0:1]
	s_add_i32 m0, s26, 0x2000
	s_nop 0
	global_load_lds_dwordx4 v[132:133], off
	v_lshl_add_u64 v[132:133], v[140:141], 0, s[46:47]
	s_mov_b32 m0, s84
	s_nop 0
	global_load_lds_dwordx4 v[132:133], off
	v_lshl_add_u64 v[132:133], v[142:143], 0, s[46:47]
	s_mov_b32 m0, s76
	s_nop 0
	global_load_lds_dwordx4 v[132:133], off
	s_waitcnt vmcnt(8)
	s_waitcnt lgkmcnt(0)
	s_barrier
	s_setprio 1
	s_waitcnt lgkmcnt(0)
	v_mfma_f32_16x16x32_bf16 v[64:67], v[158:161], v[192:195], v[64:67]
	v_mfma_f32_16x16x32_bf16 v[60:63], v[168:171], v[192:195], v[60:63]
	v_mfma_f32_16x16x32_bf16 v[56:59], v[158:161], v[214:217], v[56:59]
	v_mfma_f32_16x16x32_bf16 v[48:51], v[168:171], v[214:217], v[48:51]
	v_mfma_f32_16x16x32_bf16 v[40:43], v[158:161], v[222:225], v[40:43]
	v_mfma_f32_16x16x32_bf16 v[32:35], v[168:171], v[222:225], v[32:35]
	v_mfma_f32_16x16x32_bf16 v[24:27], v[158:161], v[230:233], v[24:27]
	v_mfma_f32_16x16x32_bf16 v[16:19], v[168:171], v[230:233], v[16:19]
	v_mfma_f32_16x16x32_bf16 v[64:67], v[164:167], v[196:199], v[64:67]
	v_mfma_f32_16x16x32_bf16 v[60:63], v[172:175], v[196:199], v[60:63]
	v_mfma_f32_16x16x32_bf16 v[56:59], v[164:167], v[218:221], v[56:59]
	v_mfma_f32_16x16x32_bf16 v[48:51], v[172:175], v[218:221], v[48:51]
	v_mfma_f32_16x16x32_bf16 v[40:43], v[164:167], v[226:229], v[40:43]
	v_mfma_f32_16x16x32_bf16 v[32:35], v[172:175], v[226:229], v[32:35]
	v_mfma_f32_16x16x32_bf16 v[24:27], v[164:167], v[234:237], v[24:27]
	v_mfma_f32_16x16x32_bf16 v[16:19], v[172:175], v[234:237], v[16:19]
	s_setprio 0
	s_setprio 1
	v_mfma_f32_16x16x32_bf16 v[52:55], v[176:179], v[192:195], v[52:55]
	v_mfma_f32_16x16x32_bf16 v[44:47], v[184:187], v[192:195], v[44:47]
	v_mfma_f32_16x16x32_bf16 v[36:39], v[176:179], v[214:217], v[36:39]
	v_mfma_f32_16x16x32_bf16 v[28:31], v[184:187], v[214:217], v[28:31]
	v_mfma_f32_16x16x32_bf16 v[20:23], v[176:179], v[222:225], v[20:23]
	v_mfma_f32_16x16x32_bf16 v[12:15], v[184:187], v[222:225], v[12:15]
	v_mfma_f32_16x16x32_bf16 v[8:11], v[176:179], v[230:233], v[8:11]
	v_mfma_f32_16x16x32_bf16 v[4:7], v[184:187], v[230:233], v[4:7]
	v_mfma_f32_16x16x32_bf16 v[52:55], v[180:183], v[196:199], v[52:55]
	v_mfma_f32_16x16x32_bf16 v[44:47], v[188:191], v[196:199], v[44:47]
	v_mfma_f32_16x16x32_bf16 v[36:39], v[180:183], v[218:221], v[36:39]
	v_mfma_f32_16x16x32_bf16 v[28:31], v[188:191], v[218:221], v[28:31]
	v_mfma_f32_16x16x32_bf16 v[20:23], v[180:183], v[226:229], v[20:23]
	v_mfma_f32_16x16x32_bf16 v[12:15], v[188:191], v[226:229], v[12:15]
	v_mfma_f32_16x16x32_bf16 v[8:11], v[180:183], v[234:237], v[8:11]
	v_mfma_f32_16x16x32_bf16 v[4:7], v[188:191], v[234:237], v[4:7]
	s_setprio 0
	s_barrier
	s_add_i32 s45, s45, 2
	s_add_u32 s42, s42, 0x100
	s_addc_u32 s44, s44, 0
	s_add_u32 s20, s20, 0x100
	s_addc_u32 s21, s21, 0
	s_cmp_gt_u32 s45, 13
	s_cbranch_scc0 .LBB0_601
	s_cmp_gt_i32 s35, 10
	s_mov_b64 s[20:21], -1
	s_mov_b32 s26, 0x1a000
	s_mov_b32 s27, 0x19000
	s_cbranch_scc0 .LBB0_604
; __device__ __forceinline__ unsigned pk2(float lo, float hi) { unsigned r; asm("v_cvt_pk_bf16_f32 %0, %1, %2" : "=v"(r) : "v"(lo), "v"(hi)); return r; }
;     __device__ __forceinline__ void operator()(const f32x4 (&acc)[2][2][4][2], const Unit& u, int wr, int wc, int fr, int fq) const {
;     ...
;             const int g = u.pn - 11, n = g >> 2, q = g & 3;
;             bf16_t* blk = Gt + (((size_t)n * 64 + u.pm) * 8 + q * 2) * 32768 + (size_t)((wr * 4 * 4 + wc) * 64 + fq * 16 + fr) * 8;
; #pragma unroll
;             for (int ai = 0; ai < 2; ++ai)
; #pragma unroll
;                 for (int m = 0; m < 4; ++m)
; #pragma unroll
;                     for (int bj = 0; bj < 2; ++bj) { const f32x4 v0 = acc[ai][bj][m][0], v1 = acc[ai][bj][m][1];
;                         u32x4 w; w.x = pk2(v0[0], v0[1]); w.y = pk2(v0[2], v0[3]); w.z = pk2(v1[0], v1[1]); w.w = pk2(v1[2], v1[3]);
;                         *(u32x4*)(blk + (size_t)bj * 32768 + (size_t)((ai * 8 + m) * 4) * 512) = w; }
	s_add_i32 s9, s35, -11
	s_mov_b32 s21, s77
	s_lshr_b32 s20, s9, 2
	s_ashr_i32 s19, s18, 31
	s_lshl_b64 s[20:21], s[20:21], 9
	s_lshl_b64 s[24:25], s[18:19], 3
	s_add_u32 s11, s20, s24
	s_addc_u32 s21, s21, s25
	s_lshl_b32 s9, s9, 1
	s_and_b32 s9, s9, 6
	s_or_b32 s20, s11, s9
	s_lshl_b64 s[20:21], s[20:21], 16
	v_lshl_add_u64 v[158:159], v[152:153], 0, s[20:21]
	s_mov_b32 s9, 0x11000
	v_add_co_u32_e32 v132, vcc, s9, v158
	v_cvt_pk_bf16_f32 v164, v128, v129
	v_cvt_pk_bf16_f32 v165, v130, v131
	v_cvt_pk_bf16_f32 v166, v124, v125
	v_cvt_pk_bf16_f32 v167, v126, v127
	s_nop 1
	v_addc_co_u32_e32 v133, vcc, 0, v159, vcc
	global_store_dwordx4 v[158:159], v[164:167], off
	v_add_co_u32_e32 v134, vcc, s81, v158
	s_nop 0
	v_cvt_pk_bf16_f32 v164, v116, v117
	v_cvt_pk_bf16_f32 v165, v118, v119
	v_cvt_pk_bf16_f32 v166, v108, v109
	v_cvt_pk_bf16_f32 v167, v110, v111
	global_store_dwordx4 v[132:133], v[164:167], off offset:-4096
	v_addc_co_u32_e32 v135, vcc, 0, v159, vcc
	s_nop 0
	v_cvt_pk_bf16_f32 v164, v120, v121
	v_cvt_pk_bf16_f32 v165, v122, v123
	v_cvt_pk_bf16_f32 v166, v112, v113
	v_cvt_pk_bf16_f32 v167, v114, v115
	s_mov_b32 s9, 0x13000
	global_store_dwordx4 v[134:135], v[164:167], off offset:-4096
	s_mov_b64 s[20:21], 0
	s_nop 0
	v_cvt_pk_bf16_f32 v164, v100, v101
	v_cvt_pk_bf16_f32 v165, v102, v103
	v_cvt_pk_bf16_f32 v166, v92, v93
	v_cvt_pk_bf16_f32 v167, v94, v95
	global_store_dwordx4 v[132:133], v[164:167], off
	v_add_co_u32_e32 v132, vcc, s9, v158
	s_nop 0
	v_cvt_pk_bf16_f32 v164, v104, v105
	v_cvt_pk_bf16_f32 v165, v106, v107
	v_cvt_pk_bf16_f32 v166, v96, v97
	v_cvt_pk_bf16_f32 v167, v98, v99
	s_nop 0
	v_addc_co_u32_e32 v133, vcc, 0, v159, vcc
	global_store_dwordx4 v[134:135], v[164:167], off
	v_add_co_u32_e32 v134, vcc, s82, v158
	s_nop 0
	v_cvt_pk_bf16_f32 v164, v84, v85
	v_cvt_pk_bf16_f32 v165, v86, v87
	v_cvt_pk_bf16_f32 v166, v76, v77
	v_cvt_pk_bf16_f32 v167, v78, v79
	global_store_dwordx4 v[132:133], v[164:167], off offset:-4096
	v_addc_co_u32_e32 v135, vcc, 0, v159, vcc
	s_nop 0
	v_cvt_pk_bf16_f32 v164, v88, v89
	v_cvt_pk_bf16_f32 v165, v90, v91
	v_cvt_pk_bf16_f32 v166, v80, v81
	v_cvt_pk_bf16_f32 v167, v82, v83
	s_mov_b32 s9, 0x9000
	global_store_dwordx4 v[134:135], v[164:167], off
	s_nop 1
	v_cvt_pk_bf16_f32 v164, v72, v73
	v_cvt_pk_bf16_f32 v165, v74, v75
	v_cvt_pk_bf16_f32 v166, v68, v69
	v_cvt_pk_bf16_f32 v167, v70, v71
	global_store_dwordx4 v[132:133], v[164:167], off
	v_add_co_u32_e32 v132, vcc, s9, v158
	s_nop 0
	v_cvt_pk_bf16_f32 v164, v64, v65
	v_cvt_pk_bf16_f32 v165, v66, v67
	v_cvt_pk_bf16_f32 v166, v60, v61
	v_cvt_pk_bf16_f32 v167, v62, v63
	s_nop 0
	v_addc_co_u32_e32 v133, vcc, 0, v159, vcc
	v_add_co_u32_e32 v134, vcc, s27, v158
	global_store_dwordx4 v[132:133], v[164:167], off offset:-4096
	s_nop 0
	v_addc_co_u32_e32 v135, vcc, 0, v159, vcc
	v_cvt_pk_bf16_f32 v164, v52, v53
	v_cvt_pk_bf16_f32 v165, v54, v55
	v_cvt_pk_bf16_f32 v166, v44, v45
	v_cvt_pk_bf16_f32 v167, v46, v47
	s_mov_b32 s9, 0xb000
	global_store_dwordx4 v[134:135], v[164:167], off offset:-4096
	s_nop 1
	v_cvt_pk_bf16_f32 v164, v56, v57
	v_cvt_pk_bf16_f32 v165, v58, v59
	v_cvt_pk_bf16_f32 v166, v48, v49
	v_cvt_pk_bf16_f32 v167, v50, v51
	global_store_dwordx4 v[132:133], v[164:167], off
	v_add_co_u32_e32 v132, vcc, s9, v158
	s_nop 0
	v_cvt_pk_bf16_f32 v164, v36, v37
	v_cvt_pk_bf16_f32 v165, v38, v39
	v_cvt_pk_bf16_f32 v166, v28, v29
	v_cvt_pk_bf16_f32 v167, v30, v31
	s_nop 0
	v_addc_co_u32_e32 v133, vcc, 0, v159, vcc
	global_store_dwordx4 v[134:135], v[164:167], off
	v_add_co_u32_e32 v134, vcc, s26, v158
	s_nop 0
	v_cvt_pk_bf16_f32 v164, v40, v41
	v_cvt_pk_bf16_f32 v165, v42, v43
	v_cvt_pk_bf16_f32 v166, v32, v33
	v_cvt_pk_bf16_f32 v167, v34, v35
	global_store_dwordx4 v[132:133], v[164:167], off offset:-4096
	v_addc_co_u32_e32 v135, vcc, 0, v159, vcc
	s_nop 0
	v_cvt_pk_bf16_f32 v164, v20, v21
	v_cvt_pk_bf16_f32 v165, v22, v23
	v_cvt_pk_bf16_f32 v166, v12, v13
	v_cvt_pk_bf16_f32 v167, v14, v15
	global_store_dwordx4 v[134:135], v[164:167], off
	s_nop 1
	v_cvt_pk_bf16_f32 v164, v24, v25
	v_cvt_pk_bf16_f32 v165, v26, v27
	v_cvt_pk_bf16_f32 v166, v16, v17
	v_cvt_pk_bf16_f32 v167, v18, v19
	global_store_dwordx4 v[132:133], v[164:167], off
	v_add_co_u32_e32 v132, vcc, 0x1b000, v158
	s_nop 0
	v_cvt_pk_bf16_f32 v164, v8, v9
	v_cvt_pk_bf16_f32 v165, v10, v11
	v_cvt_pk_bf16_f32 v166, v4, v5
	v_cvt_pk_bf16_f32 v167, v6, v7
	s_nop 0
	v_addc_co_u32_e32 v133, vcc, 0, v159, vcc
	global_store_dwordx4 v[132:133], v[164:167], off
